# strategy 2 (de-serialisation): prep1 row body issues its 12 loads together and waits once instead of 8 dependent round trips per row
# speedup vs baseline: 1.0071x; 1.0071x over previous
.LBB0_399:
	s_or_b64 exec, exec, s[0:1]
	v_lshl_add_u64 v[28:29], v[16:17], 0, v[0:1]
	global_load_dwordx4 v[40:43], v[28:29], off
	global_load_dwordx4 v[44:47], v[28:29], off offset:1024
	global_load_dwordx4 v[48:51], v[28:29], off offset:2048
	global_load_dwordx4 v[52:55], v[28:29], off offset:3072
	v_lshrrev_b32_e32 v9, 10, v14
	v_add_u32_e32 v9, 1, v9
	v_mov_b64_e32 v[14:15], s[26:27]
	v_cndmask_b32_e64 v9, v9, 0, vcc
	v_mad_u64_u32 v[14:15], s[0:1], v9, s33, v[14:15]
	v_lshlrev_b64 v[20:21], 12, v[2:3]
	s_mov_b64 s[0:1], 0x1000
	v_lshl_add_u64 v[30:31], v[4:5], 0, v[20:21]
	v_lshl_add_u64 v[32:33], v[14:15], 0, s[0:1]
	v_lshl_add_u64 v[20:21], v[32:33], 0, v[0:1]
	v_lshl_add_u64 v[34:35], v[14:15], 0, v[0:1]
	v_lshlrev_b64 v[14:15], 11, v[2:3]
	v_lshl_add_u64 v[36:37], v[6:7], 0, v[14:15]
	v_add_u32_e32 v2, s6, v2
	s_movk_i32 s0, 0x17ff
	v_cmp_lt_i32_e32 vcc, s0, v2
	s_or_b64 s[34:35], vcc, s[34:35]
	global_load_dwordx4 v[56:59], v[20:21], off
	global_load_dwordx4 v[60:63], v[20:21], off offset:1024
	global_load_dwordx4 v[64:67], v[20:21], off offset:2048
	global_load_dwordx4 v[68:71], v[20:21], off offset:3072
	global_load_dwordx4 v[72:75], v[34:35], off
	global_load_dwordx4 v[76:79], v[34:35], off offset:1024
	global_load_dwordx4 v[80:83], v[34:35], off offset:2048
	global_load_dwordx4 v[84:87], v[34:35], off offset:3072
	s_waitcnt vmcnt(0)
	global_store_dwordx4 v[30:31], v[40:43], off
	v_pk_add_f32 v[56:57], v[56:57], 1.0 op_sel_hi:[1,0]
	v_pk_add_f32 v[58:59], v[58:59], 1.0 op_sel_hi:[1,0]
	v_pk_fma_f32 v[56:57], v[40:41], v[56:57], v[72:73]
	v_pk_fma_f32 v[58:59], v[42:43], v[58:59], v[74:75]
	v_cvt_pk_bf16_f32 v56, v56, v57
	v_cvt_pk_bf16_f32 v57, v58, v59
	global_store_dwordx2 v[36:37], v[56:57], off
	global_store_dwordx4 v[30:31], v[44:47], off offset:1024
	v_pk_add_f32 v[60:61], v[60:61], 1.0 op_sel_hi:[1,0]
	v_pk_add_f32 v[62:63], v[62:63], 1.0 op_sel_hi:[1,0]
	v_pk_fma_f32 v[60:61], v[44:45], v[60:61], v[76:77]
	v_pk_fma_f32 v[62:63], v[46:47], v[62:63], v[78:79]
	v_cvt_pk_bf16_f32 v60, v60, v61
	v_cvt_pk_bf16_f32 v61, v62, v63
	global_store_dwordx2 v[36:37], v[60:61], off offset:512
	global_store_dwordx4 v[30:31], v[48:51], off offset:2048
	v_pk_add_f32 v[64:65], v[64:65], 1.0 op_sel_hi:[1,0]
	v_pk_add_f32 v[66:67], v[66:67], 1.0 op_sel_hi:[1,0]
	v_pk_fma_f32 v[64:65], v[48:49], v[64:65], v[80:81]
	v_pk_fma_f32 v[66:67], v[50:51], v[66:67], v[82:83]
	v_cvt_pk_bf16_f32 v64, v64, v65
	v_cvt_pk_bf16_f32 v65, v66, v67
	global_store_dwordx2 v[36:37], v[64:65], off offset:1024
	global_store_dwordx4 v[30:31], v[52:55], off offset:3072
	v_pk_add_f32 v[68:69], v[68:69], 1.0 op_sel_hi:[1,0]
	v_pk_add_f32 v[70:71], v[70:71], 1.0 op_sel_hi:[1,0]
	v_pk_fma_f32 v[68:69], v[52:53], v[68:69], v[84:85]
	v_pk_fma_f32 v[70:71], v[54:55], v[70:71], v[86:87]
	v_cvt_pk_bf16_f32 v68, v68, v69
	v_cvt_pk_bf16_f32 v69, v70, v71
	global_store_dwordx2 v[36:37], v[68:69], off offset:1536
	s_andn2_b64 exec, exec, s[34:35]
	s_cbranch_execz .LBB0_404
